# v31 + prep maps epilogue: lane-quad 4x4 transposes (packed bf16, DPP + v_perm) so each lane stores 8 bytes (4 adjacent columns) instead of four 2-byte stores; scalar row bases
# baseline (speedup 1.0000x reference)
; DI bf16_t f2bf(float f) { return (bf16_t)cvt_pk_bf16(f, 0.f); }
; DI int crow(int i, int hh) { return (i & 3) + 8 * (i >> 2) + 4 * hh; }
; DI void prep_phase(PARAMS P, int l, int g, LAS unsigned char* lds, int wave, int lane) {
;     ...
;                     bf16_t* o = gb + (size_t)(mt == 0 ? CP_MQ : CP_MV) * G0ROWS;
; #pragma unroll
;                     for (int i = 0; i < 16; ++i) { int t0 = crow(i, hh); asm volatile("" : "+v"(t0)); o[(size_t)(row0 + t0) * 512 + e] = f2bf(a0[i]); o[(size_t)(row0 + 32 + t0) * 512 + e] = f2bf(a1[i]); }
.LBB0_748:
	s_cmp_lt_u32 s33, 16
	s_mov_b32 s4, 0x8c00000
	s_cselect_b32 s4, s4, 0xa640000
	s_add_u32 s4, s12, s4
	s_addc_u32 s5, s18, 0
	s_lshl_b32 s100, s6, 10
	s_add_u32 s4, s4, s100
	s_addc_u32 s5, s5, 0
	v_and_b32_e32 v129, 3, v235
	v_and_b32_e32 v127, 0x3f8, v32
	v_or_b32_e32 v126, v94, v129
	v_lshl_or_b32 v126, v126, 10, v127
	v_add_u32_e32 v127, 0x8000, v126
	v_and_b32_e32 v128, 2, v235
	v_cmp_ne_u32_e32 vcc, 0, v128
	v_and_b32_e32 v128, 1, v235
	v_mov_b32_e32 v129, 0x1000504
	v_mov_b32_e32 v163, 0x7060302
	v_cmp_ne_u32_e64 s[98:99], 0, v128
	s_nop 1
	v_cndmask_b32_e64 v129, v129, v163, s[98:99]
	s_nop 7
	v_cvt_pk_bf16_f32 v146, v0, v1
	v_cvt_pk_bf16_f32 v147, v2, v3
	v_cvt_pk_bf16_f32 v154, v16, v17
	v_cvt_pk_bf16_f32 v155, v18, v19
	v_mov_b32_dpp v148, v146 quad_perm:[1,0,3,2] row_mask:0xf bank_mask:0xf
	v_mov_b32_dpp v149, v147 quad_perm:[1,0,3,2] row_mask:0xf bank_mask:0xf
	v_mov_b32_dpp v156, v154 quad_perm:[1,0,3,2] row_mask:0xf bank_mask:0xf
	v_mov_b32_dpp v157, v155 quad_perm:[1,0,3,2] row_mask:0xf bank_mask:0xf
	v_perm_b32 v148, v146, v148, v129
	v_perm_b32 v149, v147, v149, v129
	v_perm_b32 v156, v154, v156, v129
	v_perm_b32 v157, v155, v157, v129
	v_mov_b32_dpp v150, v148 quad_perm:[2,3,0,1] row_mask:0xf bank_mask:0xf
	v_mov_b32_dpp v151, v149 quad_perm:[2,3,0,1] row_mask:0xf bank_mask:0xf
	v_mov_b32_dpp v158, v156 quad_perm:[2,3,0,1] row_mask:0xf bank_mask:0xf
	v_mov_b32_dpp v159, v157 quad_perm:[2,3,0,1] row_mask:0xf bank_mask:0xf
	v_cndmask_b32_e32 v152, v148, v151, vcc
	v_cndmask_b32_e32 v153, v150, v149, vcc
	v_cndmask_b32_e32 v160, v156, v159, vcc
	v_cndmask_b32_e32 v161, v158, v157, vcc
	global_store_dwordx2 v126, v[152:153], s[4:5]
	global_store_dwordx2 v127, v[160:161], s[4:5]
	s_add_u32 s4, s4, 0x2000
	s_addc_u32 s5, s5, 0
	v_cvt_pk_bf16_f32 v146, v4, v5
	v_cvt_pk_bf16_f32 v147, v6, v7
	v_cvt_pk_bf16_f32 v154, v20, v21
	v_cvt_pk_bf16_f32 v155, v22, v23
	v_mov_b32_dpp v148, v146 quad_perm:[1,0,3,2] row_mask:0xf bank_mask:0xf
	v_mov_b32_dpp v149, v147 quad_perm:[1,0,3,2] row_mask:0xf bank_mask:0xf
	v_mov_b32_dpp v156, v154 quad_perm:[1,0,3,2] row_mask:0xf bank_mask:0xf
	v_mov_b32_dpp v157, v155 quad_perm:[1,0,3,2] row_mask:0xf bank_mask:0xf
	v_perm_b32 v148, v146, v148, v129
	v_perm_b32 v149, v147, v149, v129
	v_perm_b32 v156, v154, v156, v129
	v_perm_b32 v157, v155, v157, v129
	v_mov_b32_dpp v150, v148 quad_perm:[2,3,0,1] row_mask:0xf bank_mask:0xf
	v_mov_b32_dpp v151, v149 quad_perm:[2,3,0,1] row_mask:0xf bank_mask:0xf
	v_mov_b32_dpp v158, v156 quad_perm:[2,3,0,1] row_mask:0xf bank_mask:0xf
	v_mov_b32_dpp v159, v157 quad_perm:[2,3,0,1] row_mask:0xf bank_mask:0xf
	v_cndmask_b32_e32 v152, v148, v151, vcc
	v_cndmask_b32_e32 v153, v150, v149, vcc
	v_cndmask_b32_e32 v160, v156, v159, vcc
	v_cndmask_b32_e32 v161, v158, v157, vcc
	global_store_dwordx2 v126, v[152:153], s[4:5]
	global_store_dwordx2 v127, v[160:161], s[4:5]
	s_add_u32 s4, s4, 0x2000
	s_addc_u32 s5, s5, 0
	v_cvt_pk_bf16_f32 v146, v8, v9
	v_cvt_pk_bf16_f32 v147, v10, v11
	v_cvt_pk_bf16_f32 v154, v24, v25
	v_cvt_pk_bf16_f32 v155, v26, v27
	v_mov_b32_dpp v148, v146 quad_perm:[1,0,3,2] row_mask:0xf bank_mask:0xf
	v_mov_b32_dpp v149, v147 quad_perm:[1,0,3,2] row_mask:0xf bank_mask:0xf
	v_mov_b32_dpp v156, v154 quad_perm:[1,0,3,2] row_mask:0xf bank_mask:0xf
	v_mov_b32_dpp v157, v155 quad_perm:[1,0,3,2] row_mask:0xf bank_mask:0xf
	v_perm_b32 v148, v146, v148, v129
	v_perm_b32 v149, v147, v149, v129
	v_perm_b32 v156, v154, v156, v129
	v_perm_b32 v157, v155, v157, v129
	v_mov_b32_dpp v150, v148 quad_perm:[2,3,0,1] row_mask:0xf bank_mask:0xf
	v_mov_b32_dpp v151, v149 quad_perm:[2,3,0,1] row_mask:0xf bank_mask:0xf
	v_mov_b32_dpp v158, v156 quad_perm:[2,3,0,1] row_mask:0xf bank_mask:0xf
	v_mov_b32_dpp v159, v157 quad_perm:[2,3,0,1] row_mask:0xf bank_mask:0xf
	v_cndmask_b32_e32 v152, v148, v151, vcc
	v_cndmask_b32_e32 v153, v150, v149, vcc
	v_cndmask_b32_e32 v160, v156, v159, vcc
	v_cndmask_b32_e32 v161, v158, v157, vcc
	global_store_dwordx2 v126, v[152:153], s[4:5]
	global_store_dwordx2 v127, v[160:161], s[4:5]
	s_add_u32 s4, s4, 0x2000
	s_addc_u32 s5, s5, 0
	v_cvt_pk_bf16_f32 v146, v12, v13
	v_cvt_pk_bf16_f32 v147, v14, v15
	v_cvt_pk_bf16_f32 v154, v28, v29
	v_cvt_pk_bf16_f32 v155, v30, v31
	v_mov_b32_dpp v148, v146 quad_perm:[1,0,3,2] row_mask:0xf bank_mask:0xf
	v_mov_b32_dpp v149, v147 quad_perm:[1,0,3,2] row_mask:0xf bank_mask:0xf
	v_mov_b32_dpp v156, v154 quad_perm:[1,0,3,2] row_mask:0xf bank_mask:0xf
	v_mov_b32_dpp v157, v155 quad_perm:[1,0,3,2] row_mask:0xf bank_mask:0xf
	v_perm_b32 v148, v146, v148, v129
	v_perm_b32 v149, v147, v149, v129
	v_perm_b32 v156, v154, v156, v129
	v_perm_b32 v157, v155, v157, v129
	v_mov_b32_dpp v150, v148 quad_perm:[2,3,0,1] row_mask:0xf bank_mask:0xf
	v_mov_b32_dpp v151, v149 quad_perm:[2,3,0,1] row_mask:0xf bank_mask:0xf
	v_mov_b32_dpp v158, v156 quad_perm:[2,3,0,1] row_mask:0xf bank_mask:0xf
	v_mov_b32_dpp v159, v157 quad_perm:[2,3,0,1] row_mask:0xf bank_mask:0xf
	v_cndmask_b32_e32 v152, v148, v151, vcc
	v_cndmask_b32_e32 v153, v150, v149, vcc
	v_cndmask_b32_e32 v160, v156, v159, vcc
	v_cndmask_b32_e32 v161, v158, v157, vcc
	global_store_dwordx2 v126, v[152:153], s[4:5]
	global_store_dwordx2 v127, v[160:161], s[4:5]
	s_branch .LBB0_745
; DI bf16_t f2bf(float f) { return (bf16_t)cvt_pk_bf16(f, 0.f); }
; DI int crow(int i, int hh) { return (i & 3) + 8 * (i >> 2) + 4 * hh; }
; DI void prep_phase(PARAMS P, int l, int g, LAS unsigned char* lds, int wave, int lane) {
;     ...
;                     bf16_t* mk = gb + (size_t)CP_MK * G0ROWS; bf16_t* mks = gb + (size_t)CP_MKST * G0ROWS; float dn = 0.f;
; #pragma unroll
;                     for (int i = 0; i < 16; ++i) {
;                         int t0 = crow(i, hh); asm volatile("" : "+v"(t0)); const int t1 = 32 + t0; const float k0 = a0[i] * 0.08838834764831845f, k1 = a1[i] * 0.08838834764831845f;
;                         const float w0 = WSTl[hd * 64 + t0], w1 = WSTl[hd * 64 + t1];
;                         mk[(size_t)(row0 + t0) * 512 + e] = f2bf(k0); mk[(size_t)(row0 + t1) * 512 + e] = f2bf(k1);
;                         mks[(size_t)(row0 + t0) * 512 + e] = f2bf(k0 * w0); mks[(size_t)(row0 + t1) * 512 + e] = f2bf(k1 * w1);
;                         dn += k0 * w0 + k1 * w1;
;                     }
;                     dn += __shfl_xor(dn, 32);
;                     if (hh == 0) DN[(size_t)(cid * 4 + hd) * 128 + 32 * nb + r] = dn;
.LBB0_749:
	s_add_i32 s4, s21, 0x22000
	v_lshl_add_u32 v128, v94, 2, s4
	ds_read2_b32 v[164:165], v128 offset0:0 offset1:32
	ds_read2_b32 v[166:167], v128 offset0:1 offset1:33
	ds_read2_b32 v[168:169], v128 offset0:2 offset1:34
	ds_read2_b32 v[170:171], v128 offset0:3 offset1:35
	ds_read2_b32 v[172:173], v128 offset0:8 offset1:40
	ds_read2_b32 v[174:175], v128 offset0:9 offset1:41
	ds_read2_b32 v[176:177], v128 offset0:10 offset1:42
	ds_read2_b32 v[178:179], v128 offset0:11 offset1:43
	ds_read2_b32 v[180:181], v128 offset0:16 offset1:48
	ds_read2_b32 v[182:183], v128 offset0:17 offset1:49
	ds_read2_b32 v[184:185], v128 offset0:18 offset1:50
	ds_read2_b32 v[186:187], v128 offset0:19 offset1:51
	ds_read2_b32 v[188:189], v128 offset0:24 offset1:56
	ds_read2_b32 v[190:191], v128 offset0:25 offset1:57
	ds_read2_b32 v[192:193], v128 offset0:26 offset1:58
	ds_read2_b32 v[194:195], v128 offset0:27 offset1:59
	v_and_b32_e32 v129, 3, v235
	v_and_b32_e32 v127, 0x3f8, v32
	v_or_b32_e32 v126, v94, v129
	v_lshl_or_b32 v126, v126, 10, v127
	v_add_u32_e32 v127, 0x8000, v126
	v_and_b32_e32 v128, 2, v235
	v_cmp_ne_u32_e32 vcc, 0, v128
	v_and_b32_e32 v128, 1, v235
	v_mov_b32_e32 v129, 0x1000504
	v_mov_b32_e32 v163, 0x7060302
	v_cmp_ne_u32_e64 s[98:99], 0, v128
	s_nop 1
	v_cndmask_b32_e64 v129, v129, v163, s[98:99]
	s_lshl_b32 s100, s6, 10
	s_add_u32 s4, s74, s100
	s_addc_u32 s5, s75, 0
	s_add_u32 s64, s78, s100
	s_addc_u32 s65, s79, 0
	s_waitcnt lgkmcnt(12)
	v_mul_f32_e32 v130, 0x3db504f3, v0
	v_mul_f32_e32 v134, 0x3db504f3, v16
	v_mul_f32_e32 v131, 0x3db504f3, v1
	v_mul_f32_e32 v135, 0x3db504f3, v17
	v_mul_f32_e32 v132, 0x3db504f3, v2
	v_mul_f32_e32 v136, 0x3db504f3, v18
	v_mul_f32_e32 v133, 0x3db504f3, v3
	v_mul_f32_e32 v137, 0x3db504f3, v19
	v_mul_f32_e32 v138, v130, v164
	v_mul_f32_e32 v142, v134, v165
	v_mul_f32_e32 v139, v131, v166
	v_mul_f32_e32 v143, v135, v167
	v_mul_f32_e32 v140, v132, v168
	v_mul_f32_e32 v144, v136, v169
	v_mul_f32_e32 v141, v133, v170
	v_mul_f32_e32 v145, v137, v171
	v_cvt_pk_bf16_f32 v146, v130, v131
	v_cvt_pk_bf16_f32 v147, v132, v133
	v_cvt_pk_bf16_f32 v154, v134, v135
	v_cvt_pk_bf16_f32 v155, v136, v137
	v_mov_b32_dpp v148, v146 quad_perm:[1,0,3,2] row_mask:0xf bank_mask:0xf
	v_mov_b32_dpp v149, v147 quad_perm:[1,0,3,2] row_mask:0xf bank_mask:0xf
	v_mov_b32_dpp v156, v154 quad_perm:[1,0,3,2] row_mask:0xf bank_mask:0xf
	v_mov_b32_dpp v157, v155 quad_perm:[1,0,3,2] row_mask:0xf bank_mask:0xf
	v_perm_b32 v148, v146, v148, v129
	v_perm_b32 v149, v147, v149, v129
	v_perm_b32 v156, v154, v156, v129
	v_perm_b32 v157, v155, v157, v129
	v_mov_b32_dpp v150, v148 quad_perm:[2,3,0,1] row_mask:0xf bank_mask:0xf
	v_mov_b32_dpp v151, v149 quad_perm:[2,3,0,1] row_mask:0xf bank_mask:0xf
	v_mov_b32_dpp v158, v156 quad_perm:[2,3,0,1] row_mask:0xf bank_mask:0xf
	v_mov_b32_dpp v159, v157 quad_perm:[2,3,0,1] row_mask:0xf bank_mask:0xf
	v_cndmask_b32_e32 v152, v148, v151, vcc
	v_cndmask_b32_e32 v153, v150, v149, vcc
	v_cndmask_b32_e32 v160, v156, v159, vcc
	v_cndmask_b32_e32 v161, v158, v157, vcc
	global_store_dwordx2 v126, v[152:153], s[4:5]
	global_store_dwordx2 v127, v[160:161], s[4:5]
	v_cvt_pk_bf16_f32 v146, v138, v139
	v_cvt_pk_bf16_f32 v147, v140, v141
	v_cvt_pk_bf16_f32 v154, v142, v143
	v_cvt_pk_bf16_f32 v155, v144, v145
	v_mov_b32_dpp v148, v146 quad_perm:[1,0,3,2] row_mask:0xf bank_mask:0xf
	v_mov_b32_dpp v149, v147 quad_perm:[1,0,3,2] row_mask:0xf bank_mask:0xf
	v_mov_b32_dpp v156, v154 quad_perm:[1,0,3,2] row_mask:0xf bank_mask:0xf
	v_mov_b32_dpp v157, v155 quad_perm:[1,0,3,2] row_mask:0xf bank_mask:0xf
	v_perm_b32 v148, v146, v148, v129
	v_perm_b32 v149, v147, v149, v129
	v_perm_b32 v156, v154, v156, v129
	v_perm_b32 v157, v155, v157, v129
	v_mov_b32_dpp v150, v148 quad_perm:[2,3,0,1] row_mask:0xf bank_mask:0xf
	v_mov_b32_dpp v151, v149 quad_perm:[2,3,0,1] row_mask:0xf bank_mask:0xf
	v_mov_b32_dpp v158, v156 quad_perm:[2,3,0,1] row_mask:0xf bank_mask:0xf
	v_mov_b32_dpp v159, v157 quad_perm:[2,3,0,1] row_mask:0xf bank_mask:0xf
	v_cndmask_b32_e32 v152, v148, v151, vcc
	v_cndmask_b32_e32 v153, v150, v149, vcc
	v_cndmask_b32_e32 v160, v156, v159, vcc
	v_cndmask_b32_e32 v161, v158, v157, vcc
	global_store_dwordx2 v126, v[152:153], s[64:65]
	global_store_dwordx2 v127, v[160:161], s[64:65]
	v_fmac_f32_e32 v142, v130, v164
	v_fmac_f32_e32 v143, v131, v166
	v_fmac_f32_e32 v144, v132, v168
	v_fmac_f32_e32 v145, v133, v170
	v_add_f32_e32 v162, 0, v142
	v_add_f32_e32 v162, v162, v143
	v_add_f32_e32 v162, v162, v144
	v_add_f32_e32 v162, v162, v145
	s_add_u32 s4, s4, 0x2000
	s_addc_u32 s5, s5, 0
	s_add_u32 s64, s64, 0x2000
	s_addc_u32 s65, s65, 0
	s_waitcnt lgkmcnt(8)
; DI bf16_t f2bf(float f) { return (bf16_t)cvt_pk_bf16(f, 0.f); }
; DI int crow(int i, int hh) { return (i & 3) + 8 * (i >> 2) + 4 * hh; }
; DI void prep_phase(PARAMS P, int l, int g, LAS unsigned char* lds, int wave, int lane) {
;     ...
;                 if (mt == 1) {
;                     bf16_t* mk = gb + (size_t)CP_MK * G0ROWS; bf16_t* mks = gb + (size_t)CP_MKST * G0ROWS; float dn = 0.f;
; #pragma unroll
;                     for (int i = 0; i < 16; ++i) {
;                         int t0 = crow(i, hh); asm volatile("" : "+v"(t0)); const int t1 = 32 + t0; const float k0 = a0[i] * 0.08838834764831845f, k1 = a1[i] * 0.08838834764831845f;
;                         const float w0 = WSTl[hd * 64 + t0], w1 = WSTl[hd * 64 + t1];
;                         mk[(size_t)(row0 + t0) * 512 + e] = f2bf(k0); mk[(size_t)(row0 + t1) * 512 + e] = f2bf(k1);
;                         mks[(size_t)(row0 + t0) * 512 + e] = f2bf(k0 * w0); mks[(size_t)(row0 + t1) * 512 + e] = f2bf(k1 * w1);
;                         dn += k0 * w0 + k1 * w1;
;                     }
	v_mul_f32_e32 v130, 0x3db504f3, v4
	v_mul_f32_e32 v134, 0x3db504f3, v20
	v_mul_f32_e32 v131, 0x3db504f3, v5
	v_mul_f32_e32 v135, 0x3db504f3, v21
	v_mul_f32_e32 v132, 0x3db504f3, v6
	v_mul_f32_e32 v136, 0x3db504f3, v22
	v_mul_f32_e32 v133, 0x3db504f3, v7
	v_mul_f32_e32 v137, 0x3db504f3, v23
	v_mul_f32_e32 v138, v130, v172
	v_mul_f32_e32 v142, v134, v173
	v_mul_f32_e32 v139, v131, v174
	v_mul_f32_e32 v143, v135, v175
	v_mul_f32_e32 v140, v132, v176
	v_mul_f32_e32 v144, v136, v177
	v_mul_f32_e32 v141, v133, v178
	v_mul_f32_e32 v145, v137, v179
	v_cvt_pk_bf16_f32 v146, v130, v131
	v_cvt_pk_bf16_f32 v147, v132, v133
	v_cvt_pk_bf16_f32 v154, v134, v135
	v_cvt_pk_bf16_f32 v155, v136, v137
	v_mov_b32_dpp v148, v146 quad_perm:[1,0,3,2] row_mask:0xf bank_mask:0xf
	v_mov_b32_dpp v149, v147 quad_perm:[1,0,3,2] row_mask:0xf bank_mask:0xf
	v_mov_b32_dpp v156, v154 quad_perm:[1,0,3,2] row_mask:0xf bank_mask:0xf
	v_mov_b32_dpp v157, v155 quad_perm:[1,0,3,2] row_mask:0xf bank_mask:0xf
	v_perm_b32 v148, v146, v148, v129
	v_perm_b32 v149, v147, v149, v129
	v_perm_b32 v156, v154, v156, v129
	v_perm_b32 v157, v155, v157, v129
	v_mov_b32_dpp v150, v148 quad_perm:[2,3,0,1] row_mask:0xf bank_mask:0xf
	v_mov_b32_dpp v151, v149 quad_perm:[2,3,0,1] row_mask:0xf bank_mask:0xf
	v_mov_b32_dpp v158, v156 quad_perm:[2,3,0,1] row_mask:0xf bank_mask:0xf
	v_mov_b32_dpp v159, v157 quad_perm:[2,3,0,1] row_mask:0xf bank_mask:0xf
	v_cndmask_b32_e32 v152, v148, v151, vcc
	v_cndmask_b32_e32 v153, v150, v149, vcc
	v_cndmask_b32_e32 v160, v156, v159, vcc
	v_cndmask_b32_e32 v161, v158, v157, vcc
	global_store_dwordx2 v126, v[152:153], s[4:5]
	global_store_dwordx2 v127, v[160:161], s[4:5]
	v_cvt_pk_bf16_f32 v146, v138, v139
	v_cvt_pk_bf16_f32 v147, v140, v141
	v_cvt_pk_bf16_f32 v154, v142, v143
	v_cvt_pk_bf16_f32 v155, v144, v145
	v_mov_b32_dpp v148, v146 quad_perm:[1,0,3,2] row_mask:0xf bank_mask:0xf
	v_mov_b32_dpp v149, v147 quad_perm:[1,0,3,2] row_mask:0xf bank_mask:0xf
	v_mov_b32_dpp v156, v154 quad_perm:[1,0,3,2] row_mask:0xf bank_mask:0xf
	v_mov_b32_dpp v157, v155 quad_perm:[1,0,3,2] row_mask:0xf bank_mask:0xf
	v_perm_b32 v148, v146, v148, v129
	v_perm_b32 v149, v147, v149, v129
	v_perm_b32 v156, v154, v156, v129
	v_perm_b32 v157, v155, v157, v129
	v_mov_b32_dpp v150, v148 quad_perm:[2,3,0,1] row_mask:0xf bank_mask:0xf
	v_mov_b32_dpp v151, v149 quad_perm:[2,3,0,1] row_mask:0xf bank_mask:0xf
	v_mov_b32_dpp v158, v156 quad_perm:[2,3,0,1] row_mask:0xf bank_mask:0xf
	v_mov_b32_dpp v159, v157 quad_perm:[2,3,0,1] row_mask:0xf bank_mask:0xf
	v_cndmask_b32_e32 v152, v148, v151, vcc
	v_cndmask_b32_e32 v153, v150, v149, vcc
	v_cndmask_b32_e32 v160, v156, v159, vcc
	v_cndmask_b32_e32 v161, v158, v157, vcc
	global_store_dwordx2 v126, v[152:153], s[64:65]
	global_store_dwordx2 v127, v[160:161], s[64:65]
	v_fmac_f32_e32 v142, v130, v172
	v_fmac_f32_e32 v143, v131, v174
	v_fmac_f32_e32 v144, v132, v176
	v_fmac_f32_e32 v145, v133, v178
	v_add_f32_e32 v162, v162, v142
	v_add_f32_e32 v162, v162, v143
	v_add_f32_e32 v162, v162, v144
	v_add_f32_e32 v162, v162, v145
	s_add_u32 s4, s4, 0x2000
	s_addc_u32 s5, s5, 0
	s_add_u32 s64, s64, 0x2000
	s_addc_u32 s65, s65, 0
	s_waitcnt lgkmcnt(4)
	v_mul_f32_e32 v130, 0x3db504f3, v8
	v_mul_f32_e32 v134, 0x3db504f3, v24
	v_mul_f32_e32 v131, 0x3db504f3, v9
	v_mul_f32_e32 v135, 0x3db504f3, v25
	v_mul_f32_e32 v132, 0x3db504f3, v10
	v_mul_f32_e32 v136, 0x3db504f3, v26
	v_mul_f32_e32 v133, 0x3db504f3, v11
	v_mul_f32_e32 v137, 0x3db504f3, v27
	v_mul_f32_e32 v138, v130, v180
	v_mul_f32_e32 v142, v134, v181
	v_mul_f32_e32 v139, v131, v182
	v_mul_f32_e32 v143, v135, v183
	v_mul_f32_e32 v140, v132, v184
	v_mul_f32_e32 v144, v136, v185
	v_mul_f32_e32 v141, v133, v186
	v_mul_f32_e32 v145, v137, v187
	v_cvt_pk_bf16_f32 v146, v130, v131
	v_cvt_pk_bf16_f32 v147, v132, v133
	v_cvt_pk_bf16_f32 v154, v134, v135
	v_cvt_pk_bf16_f32 v155, v136, v137
	v_mov_b32_dpp v148, v146 quad_perm:[1,0,3,2] row_mask:0xf bank_mask:0xf
	v_mov_b32_dpp v149, v147 quad_perm:[1,0,3,2] row_mask:0xf bank_mask:0xf
	v_mov_b32_dpp v156, v154 quad_perm:[1,0,3,2] row_mask:0xf bank_mask:0xf
	v_mov_b32_dpp v157, v155 quad_perm:[1,0,3,2] row_mask:0xf bank_mask:0xf
	v_perm_b32 v148, v146, v148, v129
	v_perm_b32 v149, v147, v149, v129
	v_perm_b32 v156, v154, v156, v129
	v_perm_b32 v157, v155, v157, v129
	v_mov_b32_dpp v150, v148 quad_perm:[2,3,0,1] row_mask:0xf bank_mask:0xf
	v_mov_b32_dpp v151, v149 quad_perm:[2,3,0,1] row_mask:0xf bank_mask:0xf
	v_mov_b32_dpp v158, v156 quad_perm:[2,3,0,1] row_mask:0xf bank_mask:0xf
	v_mov_b32_dpp v159, v157 quad_perm:[2,3,0,1] row_mask:0xf bank_mask:0xf
	v_cndmask_b32_e32 v152, v148, v151, vcc
	v_cndmask_b32_e32 v153, v150, v149, vcc
	v_cndmask_b32_e32 v160, v156, v159, vcc
	v_cndmask_b32_e32 v161, v158, v157, vcc
	global_store_dwordx2 v126, v[152:153], s[4:5]
	global_store_dwordx2 v127, v[160:161], s[4:5]
	v_cvt_pk_bf16_f32 v146, v138, v139
	v_cvt_pk_bf16_f32 v147, v140, v141
	v_cvt_pk_bf16_f32 v154, v142, v143
	v_cvt_pk_bf16_f32 v155, v144, v145
	v_mov_b32_dpp v148, v146 quad_perm:[1,0,3,2] row_mask:0xf bank_mask:0xf
	v_mov_b32_dpp v149, v147 quad_perm:[1,0,3,2] row_mask:0xf bank_mask:0xf
	v_mov_b32_dpp v156, v154 quad_perm:[1,0,3,2] row_mask:0xf bank_mask:0xf
	v_mov_b32_dpp v157, v155 quad_perm:[1,0,3,2] row_mask:0xf bank_mask:0xf
	v_perm_b32 v148, v146, v148, v129
	v_perm_b32 v149, v147, v149, v129
	v_perm_b32 v156, v154, v156, v129
	v_perm_b32 v157, v155, v157, v129
	v_mov_b32_dpp v150, v148 quad_perm:[2,3,0,1] row_mask:0xf bank_mask:0xf
	v_mov_b32_dpp v151, v149 quad_perm:[2,3,0,1] row_mask:0xf bank_mask:0xf
	v_mov_b32_dpp v158, v156 quad_perm:[2,3,0,1] row_mask:0xf bank_mask:0xf
	v_mov_b32_dpp v159, v157 quad_perm:[2,3,0,1] row_mask:0xf bank_mask:0xf
	v_cndmask_b32_e32 v152, v148, v151, vcc
	v_cndmask_b32_e32 v153, v150, v149, vcc
	v_cndmask_b32_e32 v160, v156, v159, vcc
	v_cndmask_b32_e32 v161, v158, v157, vcc
	global_store_dwordx2 v126, v[152:153], s[64:65]
	global_store_dwordx2 v127, v[160:161], s[64:65]
	v_fmac_f32_e32 v142, v130, v180
	v_fmac_f32_e32 v143, v131, v182
	v_fmac_f32_e32 v144, v132, v184
	v_fmac_f32_e32 v145, v133, v186
	v_add_f32_e32 v162, v162, v142
	v_add_f32_e32 v162, v162, v143
	v_add_f32_e32 v162, v162, v144
	v_add_f32_e32 v162, v162, v145
	s_add_u32 s4, s4, 0x2000
	s_addc_u32 s5, s5, 0
	s_add_u32 s64, s64, 0x2000
	s_addc_u32 s65, s65, 0
	s_waitcnt lgkmcnt(0)
; DI bf16_t f2bf(float f) { return (bf16_t)cvt_pk_bf16(f, 0.f); }
; DI int crow(int i, int hh) { return (i & 3) + 8 * (i >> 2) + 4 * hh; }
; DI void prep_phase(PARAMS P, int l, int g, LAS unsigned char* lds, int wave, int lane) {
;     ...
;                     for (int i = 0; i < 16; ++i) {
;                         int t0 = crow(i, hh); asm volatile("" : "+v"(t0)); const int t1 = 32 + t0; const float k0 = a0[i] * 0.08838834764831845f, k1 = a1[i] * 0.08838834764831845f;
;                         const float w0 = WSTl[hd * 64 + t0], w1 = WSTl[hd * 64 + t1];
;                         mk[(size_t)(row0 + t0) * 512 + e] = f2bf(k0); mk[(size_t)(row0 + t1) * 512 + e] = f2bf(k1);
;                         mks[(size_t)(row0 + t0) * 512 + e] = f2bf(k0 * w0); mks[(size_t)(row0 + t1) * 512 + e] = f2bf(k1 * w1);
;                         dn += k0 * w0 + k1 * w1;
;                     }
;                     dn += __shfl_xor(dn, 32);
;                     if (hh == 0) DN[(size_t)(cid * 4 + hd) * 128 + 32 * nb + r] = dn;
	v_mul_f32_e32 v130, 0x3db504f3, v12
	v_mul_f32_e32 v134, 0x3db504f3, v28
	v_mul_f32_e32 v131, 0x3db504f3, v13
	v_mul_f32_e32 v135, 0x3db504f3, v29
	v_mul_f32_e32 v132, 0x3db504f3, v14
	v_mul_f32_e32 v136, 0x3db504f3, v30
	v_mul_f32_e32 v133, 0x3db504f3, v15
	v_mul_f32_e32 v137, 0x3db504f3, v31
	v_mul_f32_e32 v138, v130, v188
	v_mul_f32_e32 v142, v134, v189
	v_mul_f32_e32 v139, v131, v190
	v_mul_f32_e32 v143, v135, v191
	v_mul_f32_e32 v140, v132, v192
	v_mul_f32_e32 v144, v136, v193
	v_mul_f32_e32 v141, v133, v194
	v_mul_f32_e32 v145, v137, v195
	v_cvt_pk_bf16_f32 v146, v130, v131
	v_cvt_pk_bf16_f32 v147, v132, v133
	v_cvt_pk_bf16_f32 v154, v134, v135
	v_cvt_pk_bf16_f32 v155, v136, v137
	v_mov_b32_dpp v148, v146 quad_perm:[1,0,3,2] row_mask:0xf bank_mask:0xf
	v_mov_b32_dpp v149, v147 quad_perm:[1,0,3,2] row_mask:0xf bank_mask:0xf
	v_mov_b32_dpp v156, v154 quad_perm:[1,0,3,2] row_mask:0xf bank_mask:0xf
	v_mov_b32_dpp v157, v155 quad_perm:[1,0,3,2] row_mask:0xf bank_mask:0xf
	v_perm_b32 v148, v146, v148, v129
	v_perm_b32 v149, v147, v149, v129
	v_perm_b32 v156, v154, v156, v129
	v_perm_b32 v157, v155, v157, v129
	v_mov_b32_dpp v150, v148 quad_perm:[2,3,0,1] row_mask:0xf bank_mask:0xf
	v_mov_b32_dpp v151, v149 quad_perm:[2,3,0,1] row_mask:0xf bank_mask:0xf
	v_mov_b32_dpp v158, v156 quad_perm:[2,3,0,1] row_mask:0xf bank_mask:0xf
	v_mov_b32_dpp v159, v157 quad_perm:[2,3,0,1] row_mask:0xf bank_mask:0xf
	v_cndmask_b32_e32 v152, v148, v151, vcc
	v_cndmask_b32_e32 v153, v150, v149, vcc
	v_cndmask_b32_e32 v160, v156, v159, vcc
	v_cndmask_b32_e32 v161, v158, v157, vcc
	global_store_dwordx2 v126, v[152:153], s[4:5]
	global_store_dwordx2 v127, v[160:161], s[4:5]
	v_cvt_pk_bf16_f32 v146, v138, v139
	v_cvt_pk_bf16_f32 v147, v140, v141
	v_cvt_pk_bf16_f32 v154, v142, v143
	v_cvt_pk_bf16_f32 v155, v144, v145
	v_mov_b32_dpp v148, v146 quad_perm:[1,0,3,2] row_mask:0xf bank_mask:0xf
	v_mov_b32_dpp v149, v147 quad_perm:[1,0,3,2] row_mask:0xf bank_mask:0xf
	v_mov_b32_dpp v156, v154 quad_perm:[1,0,3,2] row_mask:0xf bank_mask:0xf
	v_mov_b32_dpp v157, v155 quad_perm:[1,0,3,2] row_mask:0xf bank_mask:0xf
	v_perm_b32 v148, v146, v148, v129
	v_perm_b32 v149, v147, v149, v129
	v_perm_b32 v156, v154, v156, v129
	v_perm_b32 v157, v155, v157, v129
	v_mov_b32_dpp v150, v148 quad_perm:[2,3,0,1] row_mask:0xf bank_mask:0xf
	v_mov_b32_dpp v151, v149 quad_perm:[2,3,0,1] row_mask:0xf bank_mask:0xf
	v_mov_b32_dpp v158, v156 quad_perm:[2,3,0,1] row_mask:0xf bank_mask:0xf
	v_mov_b32_dpp v159, v157 quad_perm:[2,3,0,1] row_mask:0xf bank_mask:0xf
	v_cndmask_b32_e32 v152, v148, v151, vcc
	v_cndmask_b32_e32 v153, v150, v149, vcc
	v_cndmask_b32_e32 v160, v156, v159, vcc
	v_cndmask_b32_e32 v161, v158, v157, vcc
	global_store_dwordx2 v126, v[152:153], s[64:65]
	global_store_dwordx2 v127, v[160:161], s[64:65]
	v_fmac_f32_e32 v142, v130, v188
	v_fmac_f32_e32 v143, v131, v190
	v_fmac_f32_e32 v144, v132, v192
	v_fmac_f32_e32 v145, v133, v194
	v_add_f32_e32 v162, v162, v142
	v_add_f32_e32 v162, v162, v143
	v_add_f32_e32 v162, v162, v144
	v_add_f32_e32 v162, v162, v145
	v_and_b32_e32 v8, 64, v235
	v_xor_b32_e32 v1, 32, v235
	v_add_u32_e32 v8, 64, v8
	v_cmp_lt_i32_e32 vcc, v1, v8
	v_mov_b32_e32 v0, v162
	v_cndmask_b32_e32 v1, v235, v1, vcc
	v_lshlrev_b32_e32 v1, 2, v1
	ds_bpermute_b32 v1, v1, v0
	s_and_saveexec_b64 s[4:5], s[44:45]
	s_cbranch_execz .LBB0_744
	s_or_b32 s64, s17, s3
	s_ashr_i32 s65, s64, 31
	s_lshl_b64 s[64:65], s[64:65], 9
	s_add_u32 s17, s0, s64
	s_addc_u32 s21, s1, s65
	s_lshl_b32 s20, s20, 2
	s_add_u32 s20, s17, s20
	s_waitcnt lgkmcnt(0)
	v_add_f32_e32 v0, v0, v1
	s_addc_u32 s21, s21, 0
	global_store_dword v124, v0, s[20:21]
	s_branch .LBB0_744
